# RES epilogue stores lane-transposed via ds_bpermute using dead accumulator regs (coalesced 64B row segments)
# speedup vs baseline: 1.0051x; 1.0042x over previous
; __device__ __forceinline__ float bf_lo(unsigned w) { return __uint_as_float(w << 16); }
; __device__ __forceinline__ float bf_hi(unsigned w) { return __uint_as_float(w & 0xffff0000u); }
; __device__ __forceinline__ u32x4 pack8(const f32x4& v0, const f32x4& v1) { u32x4 w; w.x = cvt_pk_bf16(v0[0], v0[1]); w.y = cvt_pk_bf16(v0[2], v0[3]); w.z = cvt_pk_bf16(v1[0], v1[1]); w.w = cvt_pk_bf16(v1[2], v1[3]); return w; }
; __device__ __forceinline__ float sumsq8(const f32x4& v0, const f32x4& v1) { return (v0[0] * v0[0] + v0[1] * v0[1]) + (v0[2] * v0[2] + v0[3] * v0[3]) + (v1[0] * v1[0] + v1[1] * v1[1]) + (v1[2] * v1[2] + v1[3] * v1[3]); }
; __device__ __forceinline__ void epi_run(const Epi& E, f32x4 (&acc)[2][2][4][2], const Unit& u, int wr, int wc, int fr, int fq) {
;     ...
;         float* sslot = E.ssq_out + (size_t)(u.pn * 4 + wc) * M;
;         u32x4 x[2][4][2];
; #pragma unroll
;         for (int ai = 0; ai < 2; ++ai)
; #pragma unroll
;             for (int m = 0; m < 4; ++m)
; #pragma unroll
;                 for (int bj = 0; bj < 2; ++bj) x[ai][m][bj] = *(const u32x4*)(E.xin16 + (size_t)(row0 + ai * 128 + m * 16) * D + col0 + bj * 128);
; #pragma unroll
;         for (int ai = 0; ai < 2; ++ai) {
; #pragma unroll
;             for (int m = 0; m < 4; ++m) { const int row = row0 + ai * 128 + m * 16; float sq = 0.f;
; #pragma unroll
;                 for (int bj = 0; bj < 2; ++bj) { const u32x4 xx = x[ai][m][bj];
;                     const f32x4 x0 = (f32x4){bf_lo(xx.x), bf_hi(xx.x), bf_lo(xx.y), bf_hi(xx.y)} + acc[ai][bj][m][0], x1 = (f32x4){bf_lo(xx.z), bf_hi(xx.z), bf_lo(xx.w), bf_hi(xx.w)} + acc[ai][bj][m][1];
;                     sq += sumsq8(x0, x1); *(u32x4*)(E.xout16 + (size_t)row * D + col0 + bj * 128) = pack8(x0, x1); }
;                 sq += __shfl_xor(sq, 16); sq += __shfl_xor(sq, 32); if (fq == 0) sslot[row] = sq; }
.LBB0_277:
	s_cmp_gt_i32 s83, 3
	s_mov_b64 s[8:9], -1
	s_cbranch_scc0 .LBB0_295
	v_ashrrev_i32_e32 v213, 31, v212
	v_lshlrev_b64 v[228:229], 1, v[212:213]
	v_ashrrev_i32_e32 v211, 31, v210
	s_waitcnt lgkmcnt(0)
	v_lshl_add_u64 v[130:131], s[48:49], 0, v[228:229]
	v_lshlrev_b64 v[230:231], 11, v[210:211]
	v_lshl_add_u64 v[132:133], v[130:131], 0, v[230:231]
	global_load_dwordx4 v[190:193], v[132:133], off
	global_load_dwordx4 v[186:189], v[132:133], off offset:256
	v_or_b32_e32 v132, 16, v210
	v_ashrrev_i32_e32 v133, 31, v132
	v_lshlrev_b64 v[226:227], 11, v[132:133]
	v_lshl_add_u64 v[132:133], v[130:131], 0, v[226:227]
	global_load_dwordx4 v[182:185], v[132:133], off
	global_load_dwordx4 v[178:181], v[132:133], off offset:256
	v_or_b32_e32 v132, 32, v210
	v_ashrrev_i32_e32 v133, 31, v132
	v_lshlrev_b64 v[224:225], 11, v[132:133]
	v_lshl_add_u64 v[132:133], v[130:131], 0, v[224:225]
	global_load_dwordx4 v[174:177], v[132:133], off
	global_load_dwordx4 v[170:173], v[132:133], off offset:256
	v_or_b32_e32 v132, 48, v210
	v_ashrrev_i32_e32 v133, 31, v132
	s_mov_b64 s[20:21], 0x40000
	v_lshlrev_b64 v[222:223], 11, v[132:133]
	v_lshl_add_u64 v[220:221], v[230:231], 0, s[20:21]
	s_mov_b64 s[20:21], 0x48000
	v_lshl_add_u64 v[132:133], v[130:131], 0, v[222:223]
	v_lshl_add_u64 v[218:219], v[230:231], 0, s[20:21]
	s_mov_b64 s[20:21], 0x50000
	global_load_dwordx4 v[166:169], v[132:133], off
	global_load_dwordx4 v[162:165], v[132:133], off offset:256
	v_lshl_add_u64 v[132:133], v[130:131], 0, v[220:221]
	v_lshl_add_u64 v[216:217], v[230:231], 0, s[20:21]
	s_mov_b64 s[20:21], 0x58000
	global_load_dwordx4 v[158:161], v[132:133], off
	global_load_dwordx4 v[154:157], v[132:133], off offset:256
	v_lshl_add_u64 v[132:133], v[130:131], 0, v[218:219]
	v_lshl_add_u64 v[214:215], v[230:231], 0, s[20:21]
	global_load_dwordx4 v[150:153], v[132:133], off
	global_load_dwordx4 v[146:149], v[132:133], off offset:256
	v_lshl_add_u64 v[132:133], v[130:131], 0, v[216:217]
	v_lshl_add_u64 v[130:131], v[130:131], 0, v[214:215]
	global_load_dwordx4 v[142:145], v[132:133], off
	global_load_dwordx4 v[138:141], v[132:133], off offset:256
	global_load_dwordx4 v[134:137], v[130:131], off
	s_nop 0
	global_load_dwordx4 v[130:133], v[130:131], off offset:256
	v_lshl_add_u64 v[230:231], s[78:79], 0, v[230:231]
	v_lshl_add_u64 v[228:229], v[230:231], 0, v[228:229]
	v_cmp_lt_i32_e32 vcc, v233, v203
	s_lshl_b32 s2, s23, 2
	v_readlane_b32 s8, v250, 29
	v_cndmask_b32_e32 v0, v201, v233, vcc
	v_lshlrev_b32_e32 v0, 2, v0
	v_cmp_lt_i32_e32 vcc, v234, v203
	s_or_b32 s8, s2, s8
	s_ashr_i32 s9, s8, 31
	v_cndmask_b32_e32 v243, v201, v234, vcc
	v_lshlrev_b32_e32 v243, 2, v243
	s_lshl_b64 s[8:9], s[8:9], 16
	s_add_u32 s8, s76, s8
	s_addc_u32 s9, s77, s9
	s_waitcnt vmcnt(0)
	v_lshlrev_b32_e32 v244, 16, v190
	v_and_b32_e32 v245, 0xffff0000, v190
	v_lshlrev_b32_e32 v190, 16, v191
	v_and_b32_e32 v191, 0xffff0000, v191
	v_pk_add_f32 v[246:247], v[128:129], v[190:191]
	v_pk_add_f32 v[190:191], v[126:127], v[244:245]
	v_lshlrev_b32_e32 v244, 16, v192
	v_and_b32_e32 v245, 0xffff0000, v192
	v_lshlrev_b32_e32 v192, 16, v193
	v_and_b32_e32 v193, 0xffff0000, v193
	v_pk_add_f32 v[248:249], v[124:125], v[192:193]
	v_pk_add_f32 v[192:193], v[122:123], v[244:245]
	v_mul_f32_e32 v244, v191, v191
	v_mul_f32_e32 v245, v247, v247
	v_fmac_f32_e32 v244, v190, v190
	v_fmac_f32_e32 v245, v246, v246
	v_add_f32_e32 v244, v244, v245
	v_mul_f32_e32 v245, v193, v193
	v_fmac_f32_e32 v245, v192, v192
	v_cvt_pk_bf16_f32 v190, v190, v191
	v_cvt_pk_bf16_f32 v191, v246, v247
	v_cvt_pk_bf16_f32 v192, v192, v193
	v_cvt_pk_bf16_f32 v193, v248, v249
	v_lshrrev_b32_e32 v122, 2, v201
	v_and_b32_e32 v123, 3, v201
	v_lshl_add_u32 v246, v123, 4, v122
	v_lshlrev_b32_e32 v246, 2, v246
	v_and_b32_e32 v124, 15, v201
	v_sub_u32_e32 v122, v122, v124
	v_lshrrev_b32_e32 v124, 4, v201
	v_sub_u32_e32 v123, v123, v124
	v_lshlrev_b32_e32 v123, 4, v123
	v_lshlrev_b32_e32 v122, 11, v122
	v_add_u32_e32 v128, v122, v123
	v_ashrrev_i32_e32 v129, 31, v128
	v_lshl_add_u64 v[126:127], v[228:229], 0, v[128:129]
	ds_bpermute_b32 v122, v246, v190
	ds_bpermute_b32 v123, v246, v191
	ds_bpermute_b32 v124, v246, v192
	ds_bpermute_b32 v125, v246, v193
	v_add_f32_e32 v244, v245, v244
	v_mul_f32_e32 v245, v249, v249
	v_lshlrev_b32_e32 v190, 16, v186
	v_and_b32_e32 v191, 0xffff0000, v186
	v_lshlrev_b32_e32 v186, 16, v187
	v_and_b32_e32 v187, 0xffff0000, v187
	v_pk_add_f32 v[192:193], v[120:121], v[186:187]
	v_pk_add_f32 v[186:187], v[118:119], v[190:191]
	v_lshlrev_b32_e32 v190, 16, v188
	v_and_b32_e32 v191, 0xffff0000, v188
	v_lshlrev_b32_e32 v188, 16, v189
	v_and_b32_e32 v189, 0xffff0000, v189
	v_pk_add_f32 v[230:231], v[116:117], v[188:189]
	v_pk_add_f32 v[188:189], v[114:115], v[190:191]
	v_mul_f32_e32 v190, v187, v187
	v_mul_f32_e32 v191, v193, v193
	v_fmac_f32_e32 v190, v186, v186
	v_fmac_f32_e32 v191, v192, v192
	v_add_f32_e32 v190, v190, v191
	v_mul_f32_e32 v191, v189, v189
	v_fmac_f32_e32 v191, v188, v188
	v_add_f32_e32 v190, v191, v190
	v_mul_f32_e32 v191, v231, v231
	v_fmac_f32_e32 v245, v248, v248
	v_fmac_f32_e32 v191, v230, v230
	v_add_f32_e32 v244, v245, v244
	v_add_f32_e32 v190, v191, v190
	v_add_f32_e32 v190, v244, v190
	v_cvt_pk_bf16_f32 v186, v186, v187
	v_cvt_pk_bf16_f32 v187, v192, v193
	v_cvt_pk_bf16_f32 v188, v188, v189
	v_cvt_pk_bf16_f32 v189, v230, v231
	s_waitcnt lgkmcnt(0)
	global_store_dwordx4 v[126:127], v[122:125], off
	v_lshl_add_u64 v[126:127], v[228:229], 0, v[128:129]
	ds_bpermute_b32 v122, v246, v186
	ds_bpermute_b32 v123, v246, v187
	ds_bpermute_b32 v124, v246, v188
	ds_bpermute_b32 v125, v246, v189
	ds_bpermute_b32 v186, v0, v190
	s_waitcnt lgkmcnt(0)
	v_add_f32_e32 v188, v190, v186
	ds_bpermute_b32 v189, v243, v188
	v_lshl_add_u64 v[186:187], v[210:211], 2, s[8:9]
	s_and_saveexec_b64 s[8:9], s[40:41]
	s_cbranch_execz .LBB0_280
	s_waitcnt lgkmcnt(0)
	v_add_f32_e32 v188, v188, v189
	global_store_dword v[186:187], v188, off
; __device__ __forceinline__ float bf_lo(unsigned w) { return __uint_as_float(w << 16); }
; __device__ __forceinline__ float bf_hi(unsigned w) { return __uint_as_float(w & 0xffff0000u); }
; __device__ __forceinline__ u32x4 pack8(const f32x4& v0, const f32x4& v1) { u32x4 w; w.x = cvt_pk_bf16(v0[0], v0[1]); w.y = cvt_pk_bf16(v0[2], v0[3]); w.z = cvt_pk_bf16(v1[0], v1[1]); w.w = cvt_pk_bf16(v1[2], v1[3]); return w; }
; __device__ __forceinline__ float sumsq8(const f32x4& v0, const f32x4& v1) { return (v0[0] * v0[0] + v0[1] * v0[1]) + (v0[2] * v0[2] + v0[3] * v0[3]) + (v1[0] * v1[0] + v1[1] * v1[1]) + (v1[2] * v1[2] + v1[3] * v1[3]); }
; __device__ __forceinline__ void epi_run(const Epi& E, f32x4 (&acc)[2][2][4][2], const Unit& u, int wr, int wc, int fr, int fq) {
;     ...
;             for (int m = 0; m < 4; ++m) { const int row = row0 + ai * 128 + m * 16; float sq = 0.f;
; #pragma unroll
;                 for (int bj = 0; bj < 2; ++bj) { const u32x4 xx = x[ai][m][bj];
;                     const f32x4 x0 = (f32x4){bf_lo(xx.x), bf_hi(xx.x), bf_lo(xx.y), bf_hi(xx.y)} + acc[ai][bj][m][0], x1 = (f32x4){bf_lo(xx.z), bf_hi(xx.z), bf_lo(xx.w), bf_hi(xx.w)} + acc[ai][bj][m][1];
;                     sq += sumsq8(x0, x1); *(u32x4*)(E.xout16 + (size_t)row * D + col0 + bj * 128) = pack8(x0, x1); }
;                 sq += __shfl_xor(sq, 16); sq += __shfl_xor(sq, 32); if (fq == 0) sslot[row] = sq; }
.LBB0_280:
	s_or_b64 exec, exec, s[8:9]
	v_lshlrev_b32_e32 v188, 16, v182
	s_waitcnt lgkmcnt(0)
	v_and_b32_e32 v189, 0xffff0000, v182
	v_lshlrev_b32_e32 v182, 16, v183
	v_and_b32_e32 v183, 0xffff0000, v183
	v_pk_add_f32 v[190:191], v[112:113], v[182:183]
	v_pk_add_f32 v[182:183], v[110:111], v[188:189]
	v_lshlrev_b32_e32 v188, 16, v184
	v_and_b32_e32 v189, 0xffff0000, v184
	v_lshlrev_b32_e32 v184, 16, v185
	v_and_b32_e32 v185, 0xffff0000, v185
	v_pk_add_f32 v[192:193], v[108:109], v[184:185]
	v_pk_add_f32 v[184:185], v[106:107], v[188:189]
	v_mul_f32_e32 v188, v183, v183
	v_mul_f32_e32 v189, v191, v191
	v_fmac_f32_e32 v188, v182, v182
	v_fmac_f32_e32 v189, v190, v190
	v_add_f32_e32 v188, v188, v189
	v_mul_f32_e32 v189, v185, v185
	v_fmac_f32_e32 v189, v184, v184
	v_add_f32_e32 v188, v189, v188
	v_mul_f32_e32 v189, v193, v193
	v_fmac_f32_e32 v189, v192, v192
	v_add_f32_e32 v211, v189, v188
	v_lshl_add_u64 v[188:189], s[78:79], 0, v[226:227]
	v_cvt_pk_bf16_f32 v182, v182, v183
	v_cvt_pk_bf16_f32 v183, v190, v191
	v_cvt_pk_bf16_f32 v184, v184, v185
	v_cvt_pk_bf16_f32 v185, v192, v193
	v_lshl_add_u64 v[188:189], v[212:213], 1, v[188:189]
	s_waitcnt lgkmcnt(0)
	global_store_dwordx4 v[126:127], v[122:125], off offset:256
	v_lshl_add_u64 v[126:127], v[188:189], 0, v[128:129]
	ds_bpermute_b32 v122, v246, v182
	ds_bpermute_b32 v123, v246, v183
	ds_bpermute_b32 v124, v246, v184
	ds_bpermute_b32 v125, v246, v185
	s_nop 1
	v_lshlrev_b32_e32 v182, 16, v178
	v_and_b32_e32 v183, 0xffff0000, v178
	v_lshlrev_b32_e32 v178, 16, v179
	v_and_b32_e32 v179, 0xffff0000, v179
	v_pk_add_f32 v[184:185], v[104:105], v[178:179]
	v_pk_add_f32 v[178:179], v[102:103], v[182:183]
	v_lshlrev_b32_e32 v182, 16, v180
	v_and_b32_e32 v183, 0xffff0000, v180
	v_lshlrev_b32_e32 v180, 16, v181
	v_and_b32_e32 v181, 0xffff0000, v181
	v_pk_add_f32 v[190:191], v[96:97], v[180:181]
	v_pk_add_f32 v[180:181], v[94:95], v[182:183]
	v_mul_f32_e32 v182, v179, v179
	v_mul_f32_e32 v183, v185, v185
	v_fmac_f32_e32 v182, v178, v178
	v_fmac_f32_e32 v183, v184, v184
	v_add_f32_e32 v182, v182, v183
	v_mul_f32_e32 v183, v181, v181
	v_fmac_f32_e32 v183, v180, v180
	v_add_f32_e32 v182, v183, v182
	v_mul_f32_e32 v183, v191, v191
	v_fmac_f32_e32 v183, v190, v190
	v_add_f32_e32 v182, v183, v182
	v_add_f32_e32 v182, v211, v182
	v_cvt_pk_bf16_f32 v178, v178, v179
	v_cvt_pk_bf16_f32 v179, v184, v185
	v_cvt_pk_bf16_f32 v180, v180, v181
	v_cvt_pk_bf16_f32 v181, v190, v191
	s_waitcnt lgkmcnt(0)
	global_store_dwordx4 v[126:127], v[122:125], off
	v_lshl_add_u64 v[126:127], v[188:189], 0, v[128:129]
	ds_bpermute_b32 v122, v246, v178
	ds_bpermute_b32 v123, v246, v179
	ds_bpermute_b32 v124, v246, v180
	ds_bpermute_b32 v125, v246, v181
	ds_bpermute_b32 v178, v0, v182
	s_waitcnt lgkmcnt(0)
	v_add_f32_e32 v178, v182, v178
	ds_bpermute_b32 v179, v243, v178
	s_and_saveexec_b64 s[8:9], s[40:41]
	s_cbranch_execz .LBB0_282
	s_waitcnt lgkmcnt(0)
	v_add_f32_e32 v178, v178, v179
	global_store_dword v[186:187], v178, off offset:64
.LBB0_282:
	s_or_b64 exec, exec, s[8:9]
	v_lshlrev_b32_e32 v178, 16, v174
	s_waitcnt lgkmcnt(0)
	v_and_b32_e32 v179, 0xffff0000, v174
	v_lshlrev_b32_e32 v174, 16, v175
	v_and_b32_e32 v175, 0xffff0000, v175
	v_pk_add_f32 v[180:181], v[100:101], v[174:175]
	v_pk_add_f32 v[174:175], v[98:99], v[178:179]
	v_lshlrev_b32_e32 v178, 16, v176
	v_and_b32_e32 v179, 0xffff0000, v176
	v_lshlrev_b32_e32 v176, 16, v177
	v_and_b32_e32 v177, 0xffff0000, v177
	v_pk_add_f32 v[182:183], v[92:93], v[176:177]
	v_pk_add_f32 v[176:177], v[90:91], v[178:179]
	v_mul_f32_e32 v178, v175, v175
	v_mul_f32_e32 v179, v181, v181
	v_fmac_f32_e32 v178, v174, v174
	v_fmac_f32_e32 v179, v180, v180
	v_add_f32_e32 v178, v178, v179
	v_mul_f32_e32 v179, v177, v177
	v_fmac_f32_e32 v179, v176, v176
	v_add_f32_e32 v178, v179, v178
	v_mul_f32_e32 v179, v183, v183
	v_fmac_f32_e32 v179, v182, v182
	v_add_f32_e32 v184, v179, v178
	v_lshl_add_u64 v[178:179], s[78:79], 0, v[224:225]
	v_cvt_pk_bf16_f32 v174, v174, v175
	v_cvt_pk_bf16_f32 v175, v180, v181
	v_cvt_pk_bf16_f32 v176, v176, v177
	v_cvt_pk_bf16_f32 v177, v182, v183
	v_lshl_add_u64 v[178:179], v[212:213], 1, v[178:179]
	s_waitcnt lgkmcnt(0)
	global_store_dwordx4 v[126:127], v[122:125], off offset:256
	v_lshl_add_u64 v[126:127], v[178:179], 0, v[128:129]
	ds_bpermute_b32 v122, v246, v174
	ds_bpermute_b32 v123, v246, v175
	ds_bpermute_b32 v124, v246, v176
	ds_bpermute_b32 v125, v246, v177
	s_nop 1
	v_lshlrev_b32_e32 v174, 16, v170
	v_and_b32_e32 v175, 0xffff0000, v170
	v_lshlrev_b32_e32 v170, 16, v171
	v_and_b32_e32 v171, 0xffff0000, v171
	v_pk_add_f32 v[176:177], v[88:89], v[170:171]
	v_pk_add_f32 v[170:171], v[86:87], v[174:175]
	v_lshlrev_b32_e32 v174, 16, v172
	v_and_b32_e32 v175, 0xffff0000, v172
	v_lshlrev_b32_e32 v172, 16, v173
	v_and_b32_e32 v173, 0xffff0000, v173
	v_pk_add_f32 v[180:181], v[80:81], v[172:173]
	v_pk_add_f32 v[172:173], v[78:79], v[174:175]
	v_mul_f32_e32 v174, v171, v171
	v_mul_f32_e32 v175, v177, v177
	v_fmac_f32_e32 v174, v170, v170
	v_fmac_f32_e32 v175, v176, v176
	v_add_f32_e32 v174, v174, v175
	v_mul_f32_e32 v175, v173, v173
	v_fmac_f32_e32 v175, v172, v172
	v_add_f32_e32 v174, v175, v174
	v_mul_f32_e32 v175, v181, v181
	v_fmac_f32_e32 v175, v180, v180
	v_add_f32_e32 v174, v175, v174
	v_add_f32_e32 v174, v184, v174
	v_cvt_pk_bf16_f32 v170, v170, v171
	v_cvt_pk_bf16_f32 v171, v176, v177
	v_cvt_pk_bf16_f32 v172, v172, v173
	v_cvt_pk_bf16_f32 v173, v180, v181
	s_waitcnt lgkmcnt(0)
	global_store_dwordx4 v[126:127], v[122:125], off
	v_lshl_add_u64 v[126:127], v[178:179], 0, v[128:129]
	ds_bpermute_b32 v122, v246, v170
	ds_bpermute_b32 v123, v246, v171
	ds_bpermute_b32 v124, v246, v172
	ds_bpermute_b32 v125, v246, v173
	ds_bpermute_b32 v170, v0, v174
	s_waitcnt lgkmcnt(0)
	v_add_f32_e32 v170, v174, v170
	ds_bpermute_b32 v171, v243, v170
	s_and_saveexec_b64 s[8:9], s[40:41]
	s_cbranch_execz .LBB0_284
	s_waitcnt lgkmcnt(0)
	v_add_f32_e32 v170, v170, v171
	global_store_dword v[186:187], v170, off offset:128
; __device__ __forceinline__ float bf_lo(unsigned w) { return __uint_as_float(w << 16); }
; __device__ __forceinline__ float bf_hi(unsigned w) { return __uint_as_float(w & 0xffff0000u); }
; __device__ __forceinline__ u32x4 pack8(const f32x4& v0, const f32x4& v1) { u32x4 w; w.x = cvt_pk_bf16(v0[0], v0[1]); w.y = cvt_pk_bf16(v0[2], v0[3]); w.z = cvt_pk_bf16(v1[0], v1[1]); w.w = cvt_pk_bf16(v1[2], v1[3]); return w; }
; __device__ __forceinline__ float sumsq8(const f32x4& v0, const f32x4& v1) { return (v0[0] * v0[0] + v0[1] * v0[1]) + (v0[2] * v0[2] + v0[3] * v0[3]) + (v1[0] * v1[0] + v1[1] * v1[1]) + (v1[2] * v1[2] + v1[3] * v1[3]); }
; __device__ __forceinline__ void epi_run(const Epi& E, f32x4 (&acc)[2][2][4][2], const Unit& u, int wr, int wc, int fr, int fq) {
;     ...
;             for (int m = 0; m < 4; ++m) { const int row = row0 + ai * 128 + m * 16; float sq = 0.f;
; #pragma unroll
;                 for (int bj = 0; bj < 2; ++bj) { const u32x4 xx = x[ai][m][bj];
;                     const f32x4 x0 = (f32x4){bf_lo(xx.x), bf_hi(xx.x), bf_lo(xx.y), bf_hi(xx.y)} + acc[ai][bj][m][0], x1 = (f32x4){bf_lo(xx.z), bf_hi(xx.z), bf_lo(xx.w), bf_hi(xx.w)} + acc[ai][bj][m][1];
;                     sq += sumsq8(x0, x1); *(u32x4*)(E.xout16 + (size_t)row * D + col0 + bj * 128) = pack8(x0, x1); }
;                 sq += __shfl_xor(sq, 16); sq += __shfl_xor(sq, 32); if (fq == 0) sslot[row] = sq; }
.LBB0_284:
	s_or_b64 exec, exec, s[8:9]
	v_lshlrev_b32_e32 v170, 16, v166
	s_waitcnt lgkmcnt(0)
	v_and_b32_e32 v171, 0xffff0000, v166
	v_lshlrev_b32_e32 v166, 16, v167
	v_and_b32_e32 v167, 0xffff0000, v167
	v_pk_add_f32 v[172:173], v[84:85], v[166:167]
	v_pk_add_f32 v[166:167], v[82:83], v[170:171]
	v_lshlrev_b32_e32 v170, 16, v168
	v_and_b32_e32 v171, 0xffff0000, v168
	v_lshlrev_b32_e32 v168, 16, v169
	v_and_b32_e32 v169, 0xffff0000, v169
	v_pk_add_f32 v[174:175], v[76:77], v[168:169]
	v_pk_add_f32 v[168:169], v[74:75], v[170:171]
	v_mul_f32_e32 v170, v167, v167
	v_mul_f32_e32 v171, v173, v173
	v_fmac_f32_e32 v170, v166, v166
	v_fmac_f32_e32 v171, v172, v172
	v_add_f32_e32 v170, v170, v171
	v_mul_f32_e32 v171, v169, v169
	v_fmac_f32_e32 v171, v168, v168
	v_add_f32_e32 v170, v171, v170
	v_mul_f32_e32 v171, v175, v175
	v_fmac_f32_e32 v171, v174, v174
	v_add_f32_e32 v176, v171, v170
	v_lshl_add_u64 v[170:171], s[78:79], 0, v[222:223]
	v_cvt_pk_bf16_f32 v166, v166, v167
	v_cvt_pk_bf16_f32 v167, v172, v173
	v_cvt_pk_bf16_f32 v168, v168, v169
	v_cvt_pk_bf16_f32 v169, v174, v175
	v_lshl_add_u64 v[170:171], v[212:213], 1, v[170:171]
	s_waitcnt lgkmcnt(0)
	global_store_dwordx4 v[126:127], v[122:125], off offset:256
	v_lshl_add_u64 v[126:127], v[170:171], 0, v[128:129]
	ds_bpermute_b32 v122, v246, v166
	ds_bpermute_b32 v123, v246, v167
	ds_bpermute_b32 v124, v246, v168
	ds_bpermute_b32 v125, v246, v169
	s_nop 1
	v_lshlrev_b32_e32 v166, 16, v162
	v_and_b32_e32 v167, 0xffff0000, v162
	v_lshlrev_b32_e32 v162, 16, v163
	v_and_b32_e32 v163, 0xffff0000, v163
	v_pk_add_f32 v[168:169], v[72:73], v[162:163]
	v_pk_add_f32 v[162:163], v[70:71], v[166:167]
	v_lshlrev_b32_e32 v166, 16, v164
	v_and_b32_e32 v167, 0xffff0000, v164
	v_lshlrev_b32_e32 v164, 16, v165
	v_and_b32_e32 v165, 0xffff0000, v165
	v_pk_add_f32 v[172:173], v[68:69], v[164:165]
	v_pk_add_f32 v[164:165], v[66:67], v[166:167]
	v_mul_f32_e32 v166, v163, v163
	v_mul_f32_e32 v167, v169, v169
	v_fmac_f32_e32 v166, v162, v162
	v_fmac_f32_e32 v167, v168, v168
	v_add_f32_e32 v166, v166, v167
	v_mul_f32_e32 v167, v165, v165
	v_fmac_f32_e32 v167, v164, v164
	v_add_f32_e32 v166, v167, v166
	v_mul_f32_e32 v167, v173, v173
	v_fmac_f32_e32 v167, v172, v172
	v_add_f32_e32 v166, v167, v166
	v_add_f32_e32 v166, v176, v166
	v_cvt_pk_bf16_f32 v162, v162, v163
	v_cvt_pk_bf16_f32 v163, v168, v169
	v_cvt_pk_bf16_f32 v164, v164, v165
	v_cvt_pk_bf16_f32 v165, v172, v173
	s_waitcnt lgkmcnt(0)
	global_store_dwordx4 v[126:127], v[122:125], off
	v_lshl_add_u64 v[126:127], v[170:171], 0, v[128:129]
	ds_bpermute_b32 v122, v246, v162
	ds_bpermute_b32 v123, v246, v163
	ds_bpermute_b32 v124, v246, v164
	ds_bpermute_b32 v125, v246, v165
	ds_bpermute_b32 v162, v0, v166
	s_waitcnt lgkmcnt(0)
	v_add_f32_e32 v162, v166, v162
	ds_bpermute_b32 v163, v243, v162
	s_and_saveexec_b64 s[8:9], s[40:41]
	s_cbranch_execz .LBB0_286
	s_waitcnt lgkmcnt(0)
	v_add_f32_e32 v162, v162, v163
	global_store_dword v[186:187], v162, off offset:192
.LBB0_286:
	s_or_b64 exec, exec, s[8:9]
	v_lshlrev_b32_e32 v162, 16, v158
	s_waitcnt lgkmcnt(0)
	v_and_b32_e32 v163, 0xffff0000, v158
	v_lshlrev_b32_e32 v158, 16, v159
	v_and_b32_e32 v159, 0xffff0000, v159
	v_pk_add_f32 v[164:165], v[64:65], v[158:159]
	v_pk_add_f32 v[158:159], v[62:63], v[162:163]
	v_lshlrev_b32_e32 v162, 16, v160
	v_and_b32_e32 v163, 0xffff0000, v160
	v_lshlrev_b32_e32 v160, 16, v161
	v_and_b32_e32 v161, 0xffff0000, v161
	v_pk_add_f32 v[166:167], v[60:61], v[160:161]
	v_pk_add_f32 v[160:161], v[58:59], v[162:163]
	v_mul_f32_e32 v162, v159, v159
	v_mul_f32_e32 v163, v165, v165
	v_fmac_f32_e32 v162, v158, v158
	v_fmac_f32_e32 v163, v164, v164
	v_add_f32_e32 v162, v162, v163
	v_mul_f32_e32 v163, v161, v161
	v_fmac_f32_e32 v163, v160, v160
	v_add_f32_e32 v162, v163, v162
	v_mul_f32_e32 v163, v167, v167
	v_fmac_f32_e32 v163, v166, v166
	v_add_f32_e32 v168, v163, v162
	v_lshl_add_u64 v[162:163], s[78:79], 0, v[220:221]
	v_cvt_pk_bf16_f32 v158, v158, v159
	v_cvt_pk_bf16_f32 v159, v164, v165
	v_cvt_pk_bf16_f32 v160, v160, v161
	v_cvt_pk_bf16_f32 v161, v166, v167
	v_lshl_add_u64 v[162:163], v[212:213], 1, v[162:163]
	s_waitcnt lgkmcnt(0)
	global_store_dwordx4 v[126:127], v[122:125], off offset:256
	v_lshl_add_u64 v[126:127], v[162:163], 0, v[128:129]
	ds_bpermute_b32 v122, v246, v158
	ds_bpermute_b32 v123, v246, v159
	ds_bpermute_b32 v124, v246, v160
	ds_bpermute_b32 v125, v246, v161
	s_nop 1
	v_lshlrev_b32_e32 v158, 16, v154
	v_and_b32_e32 v159, 0xffff0000, v154
	v_lshlrev_b32_e32 v154, 16, v155
	v_and_b32_e32 v155, 0xffff0000, v155
	v_pk_add_f32 v[160:161], v[56:57], v[154:155]
	v_pk_add_f32 v[154:155], v[54:55], v[158:159]
	v_lshlrev_b32_e32 v158, 16, v156
	v_and_b32_e32 v159, 0xffff0000, v156
	v_lshlrev_b32_e32 v156, 16, v157
	v_and_b32_e32 v157, 0xffff0000, v157
	v_pk_add_f32 v[164:165], v[52:53], v[156:157]
	v_pk_add_f32 v[156:157], v[50:51], v[158:159]
	v_mul_f32_e32 v158, v155, v155
	v_mul_f32_e32 v159, v161, v161
	v_fmac_f32_e32 v158, v154, v154
	v_fmac_f32_e32 v159, v160, v160
	v_add_f32_e32 v158, v158, v159
	v_mul_f32_e32 v159, v157, v157
	v_fmac_f32_e32 v159, v156, v156
	v_add_f32_e32 v158, v159, v158
	v_mul_f32_e32 v159, v165, v165
	v_fmac_f32_e32 v159, v164, v164
	v_add_f32_e32 v158, v159, v158
	v_add_f32_e32 v158, v168, v158
	v_cvt_pk_bf16_f32 v154, v154, v155
	v_cvt_pk_bf16_f32 v155, v160, v161
	v_cvt_pk_bf16_f32 v156, v156, v157
	v_cvt_pk_bf16_f32 v157, v164, v165
	s_waitcnt lgkmcnt(0)
	global_store_dwordx4 v[126:127], v[122:125], off
	v_lshl_add_u64 v[126:127], v[162:163], 0, v[128:129]
	ds_bpermute_b32 v122, v246, v154
	ds_bpermute_b32 v123, v246, v155
	ds_bpermute_b32 v124, v246, v156
	ds_bpermute_b32 v125, v246, v157
	ds_bpermute_b32 v154, v0, v158
	s_waitcnt lgkmcnt(0)
	v_add_f32_e32 v154, v158, v154
	ds_bpermute_b32 v155, v243, v154
	s_and_saveexec_b64 s[8:9], s[40:41]
	s_cbranch_execz .LBB0_288
	s_waitcnt lgkmcnt(0)
	v_add_f32_e32 v154, v154, v155
	global_store_dword v[186:187], v154, off offset:512
; __device__ __forceinline__ float bf_lo(unsigned w) { return __uint_as_float(w << 16); }
; __device__ __forceinline__ float bf_hi(unsigned w) { return __uint_as_float(w & 0xffff0000u); }
; __device__ __forceinline__ u32x4 pack8(const f32x4& v0, const f32x4& v1) { u32x4 w; w.x = cvt_pk_bf16(v0[0], v0[1]); w.y = cvt_pk_bf16(v0[2], v0[3]); w.z = cvt_pk_bf16(v1[0], v1[1]); w.w = cvt_pk_bf16(v1[2], v1[3]); return w; }
; __device__ __forceinline__ float sumsq8(const f32x4& v0, const f32x4& v1) { return (v0[0] * v0[0] + v0[1] * v0[1]) + (v0[2] * v0[2] + v0[3] * v0[3]) + (v1[0] * v1[0] + v1[1] * v1[1]) + (v1[2] * v1[2] + v1[3] * v1[3]); }
; __device__ __forceinline__ void epi_run(const Epi& E, f32x4 (&acc)[2][2][4][2], const Unit& u, int wr, int wc, int fr, int fq) {
;     ...
;             for (int m = 0; m < 4; ++m) { const int row = row0 + ai * 128 + m * 16; float sq = 0.f;
; #pragma unroll
;                 for (int bj = 0; bj < 2; ++bj) { const u32x4 xx = x[ai][m][bj];
;                     const f32x4 x0 = (f32x4){bf_lo(xx.x), bf_hi(xx.x), bf_lo(xx.y), bf_hi(xx.y)} + acc[ai][bj][m][0], x1 = (f32x4){bf_lo(xx.z), bf_hi(xx.z), bf_lo(xx.w), bf_hi(xx.w)} + acc[ai][bj][m][1];
;                     sq += sumsq8(x0, x1); *(u32x4*)(E.xout16 + (size_t)row * D + col0 + bj * 128) = pack8(x0, x1); }
;                 sq += __shfl_xor(sq, 16); sq += __shfl_xor(sq, 32); if (fq == 0) sslot[row] = sq; }
.LBB0_288:
	s_or_b64 exec, exec, s[8:9]
	v_lshlrev_b32_e32 v154, 16, v150
	s_waitcnt lgkmcnt(0)
	v_and_b32_e32 v155, 0xffff0000, v150
	v_lshlrev_b32_e32 v150, 16, v151
	v_and_b32_e32 v151, 0xffff0000, v151
	v_pk_add_f32 v[156:157], v[48:49], v[150:151]
	v_pk_add_f32 v[150:151], v[46:47], v[154:155]
	v_lshlrev_b32_e32 v154, 16, v152
	v_and_b32_e32 v155, 0xffff0000, v152
	v_lshlrev_b32_e32 v152, 16, v153
	v_and_b32_e32 v153, 0xffff0000, v153
	v_pk_add_f32 v[158:159], v[44:45], v[152:153]
	v_pk_add_f32 v[152:153], v[42:43], v[154:155]
	v_mul_f32_e32 v154, v151, v151
	v_mul_f32_e32 v155, v157, v157
	v_fmac_f32_e32 v154, v150, v150
	v_fmac_f32_e32 v155, v156, v156
	v_add_f32_e32 v154, v154, v155
	v_mul_f32_e32 v155, v153, v153
	v_fmac_f32_e32 v155, v152, v152
	v_add_f32_e32 v154, v155, v154
	v_mul_f32_e32 v155, v159, v159
	v_fmac_f32_e32 v155, v158, v158
	v_add_f32_e32 v160, v155, v154
	v_lshl_add_u64 v[154:155], s[78:79], 0, v[218:219]
	v_cvt_pk_bf16_f32 v150, v150, v151
	v_cvt_pk_bf16_f32 v151, v156, v157
	v_cvt_pk_bf16_f32 v152, v152, v153
	v_cvt_pk_bf16_f32 v153, v158, v159
	v_lshl_add_u64 v[154:155], v[212:213], 1, v[154:155]
	s_waitcnt lgkmcnt(0)
	global_store_dwordx4 v[126:127], v[122:125], off offset:256
	v_lshl_add_u64 v[126:127], v[154:155], 0, v[128:129]
	ds_bpermute_b32 v122, v246, v150
	ds_bpermute_b32 v123, v246, v151
	ds_bpermute_b32 v124, v246, v152
	ds_bpermute_b32 v125, v246, v153
	s_nop 1
	v_lshlrev_b32_e32 v150, 16, v146
	v_and_b32_e32 v151, 0xffff0000, v146
	v_lshlrev_b32_e32 v146, 16, v147
	v_and_b32_e32 v147, 0xffff0000, v147
	v_pk_add_f32 v[152:153], v[40:41], v[146:147]
	v_pk_add_f32 v[146:147], v[38:39], v[150:151]
	v_lshlrev_b32_e32 v150, 16, v148
	v_and_b32_e32 v151, 0xffff0000, v148
	v_lshlrev_b32_e32 v148, 16, v149
	v_and_b32_e32 v149, 0xffff0000, v149
	v_pk_add_f32 v[156:157], v[36:37], v[148:149]
	v_pk_add_f32 v[148:149], v[34:35], v[150:151]
	v_mul_f32_e32 v150, v147, v147
	v_mul_f32_e32 v151, v153, v153
	v_fmac_f32_e32 v150, v146, v146
	v_fmac_f32_e32 v151, v152, v152
	v_add_f32_e32 v150, v150, v151
	v_mul_f32_e32 v151, v149, v149
	v_fmac_f32_e32 v151, v148, v148
	v_add_f32_e32 v150, v151, v150
	v_mul_f32_e32 v151, v157, v157
	v_fmac_f32_e32 v151, v156, v156
	v_add_f32_e32 v150, v151, v150
	v_add_f32_e32 v150, v160, v150
	v_cvt_pk_bf16_f32 v146, v146, v147
	v_cvt_pk_bf16_f32 v147, v152, v153
	v_cvt_pk_bf16_f32 v148, v148, v149
	v_cvt_pk_bf16_f32 v149, v156, v157
	s_waitcnt lgkmcnt(0)
	global_store_dwordx4 v[126:127], v[122:125], off
	v_lshl_add_u64 v[126:127], v[154:155], 0, v[128:129]
	ds_bpermute_b32 v122, v246, v146
	ds_bpermute_b32 v123, v246, v147
	ds_bpermute_b32 v124, v246, v148
	ds_bpermute_b32 v125, v246, v149
	ds_bpermute_b32 v146, v0, v150
	s_waitcnt lgkmcnt(0)
	v_add_f32_e32 v146, v150, v146
	ds_bpermute_b32 v147, v243, v146
	s_and_saveexec_b64 s[8:9], s[40:41]
	s_cbranch_execz .LBB0_290
	s_waitcnt lgkmcnt(0)
	v_add_f32_e32 v146, v146, v147
	global_store_dword v[186:187], v146, off offset:576
.LBB0_290:
	s_or_b64 exec, exec, s[8:9]
	v_lshlrev_b32_e32 v146, 16, v142
	s_waitcnt lgkmcnt(0)
	v_and_b32_e32 v147, 0xffff0000, v142
	v_lshlrev_b32_e32 v142, 16, v143
	v_and_b32_e32 v143, 0xffff0000, v143
	v_pk_add_f32 v[148:149], v[32:33], v[142:143]
	v_pk_add_f32 v[142:143], v[30:31], v[146:147]
	v_lshlrev_b32_e32 v146, 16, v144
	v_and_b32_e32 v147, 0xffff0000, v144
	v_lshlrev_b32_e32 v144, 16, v145
	v_and_b32_e32 v145, 0xffff0000, v145
	v_pk_add_f32 v[150:151], v[28:29], v[144:145]
	v_pk_add_f32 v[144:145], v[26:27], v[146:147]
	v_mul_f32_e32 v146, v143, v143
	v_mul_f32_e32 v147, v149, v149
	v_fmac_f32_e32 v146, v142, v142
	v_fmac_f32_e32 v147, v148, v148
	v_add_f32_e32 v146, v146, v147
	v_mul_f32_e32 v147, v145, v145
	v_fmac_f32_e32 v147, v144, v144
	v_add_f32_e32 v146, v147, v146
	v_mul_f32_e32 v147, v151, v151
	v_fmac_f32_e32 v147, v150, v150
	v_add_f32_e32 v152, v147, v146
	v_lshl_add_u64 v[146:147], s[78:79], 0, v[216:217]
	v_cvt_pk_bf16_f32 v142, v142, v143
	v_cvt_pk_bf16_f32 v143, v148, v149
	v_cvt_pk_bf16_f32 v144, v144, v145
	v_cvt_pk_bf16_f32 v145, v150, v151
	v_lshl_add_u64 v[146:147], v[212:213], 1, v[146:147]
	s_waitcnt lgkmcnt(0)
	global_store_dwordx4 v[126:127], v[122:125], off offset:256
	v_lshl_add_u64 v[126:127], v[146:147], 0, v[128:129]
	ds_bpermute_b32 v122, v246, v142
	ds_bpermute_b32 v123, v246, v143
	ds_bpermute_b32 v124, v246, v144
	ds_bpermute_b32 v125, v246, v145
	s_nop 1
	v_lshlrev_b32_e32 v142, 16, v138
	v_and_b32_e32 v143, 0xffff0000, v138
	v_lshlrev_b32_e32 v138, 16, v139
	v_and_b32_e32 v139, 0xffff0000, v139
	v_pk_add_f32 v[144:145], v[24:25], v[138:139]
	v_pk_add_f32 v[138:139], v[22:23], v[142:143]
	v_lshlrev_b32_e32 v142, 16, v140
	v_and_b32_e32 v143, 0xffff0000, v140
	v_lshlrev_b32_e32 v140, 16, v141
	v_and_b32_e32 v141, 0xffff0000, v141
	v_pk_add_f32 v[148:149], v[20:21], v[140:141]
	v_pk_add_f32 v[140:141], v[18:19], v[142:143]
	v_mul_f32_e32 v142, v139, v139
	v_mul_f32_e32 v143, v145, v145
	v_fmac_f32_e32 v142, v138, v138
	v_fmac_f32_e32 v143, v144, v144
	v_add_f32_e32 v142, v142, v143
	v_mul_f32_e32 v143, v141, v141
	v_fmac_f32_e32 v143, v140, v140
	v_add_f32_e32 v142, v143, v142
	v_mul_f32_e32 v143, v149, v149
	v_fmac_f32_e32 v143, v148, v148
	v_add_f32_e32 v142, v143, v142
	v_add_f32_e32 v142, v152, v142
	v_cvt_pk_bf16_f32 v138, v138, v139
	v_cvt_pk_bf16_f32 v139, v144, v145
	v_cvt_pk_bf16_f32 v140, v140, v141
	v_cvt_pk_bf16_f32 v141, v148, v149
	s_waitcnt lgkmcnt(0)
	global_store_dwordx4 v[126:127], v[122:125], off
	v_lshl_add_u64 v[126:127], v[146:147], 0, v[128:129]
	ds_bpermute_b32 v122, v246, v138
	ds_bpermute_b32 v123, v246, v139
	ds_bpermute_b32 v124, v246, v140
	ds_bpermute_b32 v125, v246, v141
	ds_bpermute_b32 v138, v0, v142
	s_waitcnt lgkmcnt(0)
	v_add_f32_e32 v138, v142, v138
	ds_bpermute_b32 v139, v243, v138
	s_and_saveexec_b64 s[8:9], s[40:41]
	s_cbranch_execz .LBB0_292
	s_waitcnt lgkmcnt(0)
	v_add_f32_e32 v138, v138, v139
	global_store_dword v[186:187], v138, off offset:640
; __device__ __forceinline__ float bf_lo(unsigned w) { return __uint_as_float(w << 16); }
; __device__ __forceinline__ float bf_hi(unsigned w) { return __uint_as_float(w & 0xffff0000u); }
; __device__ __forceinline__ u32x4 pack8(const f32x4& v0, const f32x4& v1) { u32x4 w; w.x = cvt_pk_bf16(v0[0], v0[1]); w.y = cvt_pk_bf16(v0[2], v0[3]); w.z = cvt_pk_bf16(v1[0], v1[1]); w.w = cvt_pk_bf16(v1[2], v1[3]); return w; }
; __device__ __forceinline__ float sumsq8(const f32x4& v0, const f32x4& v1) { return (v0[0] * v0[0] + v0[1] * v0[1]) + (v0[2] * v0[2] + v0[3] * v0[3]) + (v1[0] * v1[0] + v1[1] * v1[1]) + (v1[2] * v1[2] + v1[3] * v1[3]); }
; __device__ __forceinline__ void epi_run(const Epi& E, f32x4 (&acc)[2][2][4][2], const Unit& u, int wr, int wc, int fr, int fq) {
;     ...
;             for (int m = 0; m < 4; ++m) { const int row = row0 + ai * 128 + m * 16; float sq = 0.f;
; #pragma unroll
;                 for (int bj = 0; bj < 2; ++bj) { const u32x4 xx = x[ai][m][bj];
;                     const f32x4 x0 = (f32x4){bf_lo(xx.x), bf_hi(xx.x), bf_lo(xx.y), bf_hi(xx.y)} + acc[ai][bj][m][0], x1 = (f32x4){bf_lo(xx.z), bf_hi(xx.z), bf_lo(xx.w), bf_hi(xx.w)} + acc[ai][bj][m][1];
;                     sq += sumsq8(x0, x1); *(u32x4*)(E.xout16 + (size_t)row * D + col0 + bj * 128) = pack8(x0, x1); }
;                 sq += __shfl_xor(sq, 16); sq += __shfl_xor(sq, 32); if (fq == 0) sslot[row] = sq; }
.LBB0_292:
	s_or_b64 exec, exec, s[8:9]
	v_lshlrev_b32_e32 v138, 16, v134
	s_waitcnt lgkmcnt(0)
	v_and_b32_e32 v139, 0xffff0000, v134
	v_lshlrev_b32_e32 v134, 16, v135
	v_and_b32_e32 v135, 0xffff0000, v135
	v_pk_add_f32 v[140:141], v[16:17], v[134:135]
	v_pk_add_f32 v[134:135], v[14:15], v[138:139]
	v_lshlrev_b32_e32 v138, 16, v136
	v_and_b32_e32 v139, 0xffff0000, v136
	v_lshlrev_b32_e32 v136, 16, v137
	v_and_b32_e32 v137, 0xffff0000, v137
	v_pk_add_f32 v[142:143], v[12:13], v[136:137]
	v_pk_add_f32 v[136:137], v[10:11], v[138:139]
	v_mul_f32_e32 v138, v135, v135
	v_mul_f32_e32 v139, v141, v141
	v_fmac_f32_e32 v138, v134, v134
	v_fmac_f32_e32 v139, v140, v140
	v_add_f32_e32 v138, v138, v139
	v_mul_f32_e32 v139, v137, v137
	v_fmac_f32_e32 v139, v136, v136
	v_add_f32_e32 v138, v139, v138
	v_mul_f32_e32 v139, v143, v143
	v_fmac_f32_e32 v139, v142, v142
	v_add_f32_e32 v144, v139, v138
	v_lshl_add_u64 v[138:139], s[78:79], 0, v[214:215]
	v_cvt_pk_bf16_f32 v134, v134, v135
	v_cvt_pk_bf16_f32 v135, v140, v141
	v_cvt_pk_bf16_f32 v136, v136, v137
	v_cvt_pk_bf16_f32 v137, v142, v143
	v_lshl_add_u64 v[138:139], v[212:213], 1, v[138:139]
	s_waitcnt lgkmcnt(0)
	global_store_dwordx4 v[126:127], v[122:125], off offset:256
	v_lshl_add_u64 v[126:127], v[138:139], 0, v[128:129]
	ds_bpermute_b32 v122, v246, v134
	ds_bpermute_b32 v123, v246, v135
	ds_bpermute_b32 v124, v246, v136
	ds_bpermute_b32 v125, v246, v137
	s_nop 1
	v_lshlrev_b32_e32 v134, 16, v130
	v_and_b32_e32 v135, 0xffff0000, v130
	v_lshlrev_b32_e32 v130, 16, v131
	v_and_b32_e32 v131, 0xffff0000, v131
	v_pk_add_f32 v[136:137], v[8:9], v[130:131]
	v_pk_add_f32 v[130:131], v[6:7], v[134:135]
	v_lshlrev_b32_e32 v134, 16, v132
	v_and_b32_e32 v135, 0xffff0000, v132
	v_lshlrev_b32_e32 v132, 16, v133
	v_and_b32_e32 v133, 0xffff0000, v133
	v_pk_add_f32 v[140:141], v[4:5], v[132:133]
	v_pk_add_f32 v[132:133], v[2:3], v[134:135]
	v_mul_f32_e32 v134, v131, v131
	v_mul_f32_e32 v135, v137, v137
	v_fmac_f32_e32 v134, v130, v130
	v_fmac_f32_e32 v135, v136, v136
	v_add_f32_e32 v134, v134, v135
	v_mul_f32_e32 v135, v133, v133
	v_fmac_f32_e32 v135, v132, v132
	v_add_f32_e32 v134, v135, v134
	v_mul_f32_e32 v135, v141, v141
	v_fmac_f32_e32 v135, v140, v140
	v_add_f32_e32 v134, v135, v134
	v_add_f32_e32 v134, v144, v134
	ds_bpermute_b32 v0, v0, v134
	v_cvt_pk_bf16_f32 v130, v130, v131
	v_cvt_pk_bf16_f32 v131, v136, v137
	v_cvt_pk_bf16_f32 v132, v132, v133
	v_cvt_pk_bf16_f32 v133, v140, v141
	s_waitcnt lgkmcnt(0)
	v_add_f32_e32 v0, v134, v0
	s_waitcnt lgkmcnt(0)
	global_store_dwordx4 v[126:127], v[122:125], off
	v_lshl_add_u64 v[126:127], v[138:139], 0, v[128:129]
	ds_bpermute_b32 v122, v246, v130
	ds_bpermute_b32 v123, v246, v131
	ds_bpermute_b32 v124, v246, v132
	ds_bpermute_b32 v125, v246, v133
	s_waitcnt lgkmcnt(0)
	global_store_dwordx4 v[126:127], v[122:125], off offset:256
	ds_bpermute_b32 v130, v243, v0
	s_and_saveexec_b64 s[8:9], s[40:41]
	s_cbranch_execz .LBB0_294
	s_waitcnt lgkmcnt(0)
	v_add_f32_e32 v0, v0, v130
	global_store_dword v[186:187], v0, off offset:704
